# bisect: widened DSA output stores only
# baseline (speedup 1.0000x reference)
; #define GAS __attribute__((address_space(1)))
; __device__ __forceinline__ unsigned pk2(float lo, float hi) { f32x2_t v = {lo, hi}; bf16x2_t b = __builtin_convertvector(v, bf16x2_t); return __builtin_bit_cast(unsigned, b); }
; __device__ __forceinline__ f32x16 mfma32(bf16x8 a, bf16x8 b, f32x16 c) { return __builtin_amdgcn_mfma_f32_32x32x16_bf16(a, b, c, 0, 0, 0); }
; __device__ __forceinline__ void dsa_unit32(const Args& a, LAS unsigned char* lds, const LAS unsigned long long* maskl, int b, int qb, int tid, int wave, int lane) {
;     ...
;     l += __shfl_xor(l, 32);
;     const float il = 1.f / l;
;     bf16x8 of[8];
; #pragma unroll
;     for (int ks = 0; ks < 8; ++ks) { const int ct = ks >> 1, o8 = 8 * (ks & 1); u32x4 w;
;         w.x = pk2(O[ct][o8 + 0] * il, O[ct][o8 + 1] * il); w.y = pk2(O[ct][o8 + 2] * il, O[ct][o8 + 3] * il);
;         w.z = pk2(O[ct][o8 + 4] * il, O[ct][o8 + 5] * il); w.w = pk2(O[ct][o8 + 6] * il, O[ct][o8 + 7] * il); of[ks] = __builtin_bit_cast(bf16x8, w); }
; #pragma unroll
;     for (int vt = 0; vt < 2; ++vt) {
;         f32x16 acc;
; #pragma unroll
;         for (int i = 0; i < 16; ++i) acc[i] = 0.f;
;         const GAS bf16* wr = wuv + (size_t)(h * 64 + 32 * vt + l31) * 128 + 4 * hi;
; #pragma unroll
;         for (int ks = 0; ks < 8; ++ks) acc = mfma32(cat8(*(const GAS u32x2*)(wr + 16 * ks), *(const GAS u32x2*)(wr + 16 * ks + 8)), of[ks], acc);
.LBB0_1073:
	v_readlane_b32 s0, v254, 32
	v_readlane_b32 s1, v254, 33
	v_lshlrev_b32_e32 v92, 1, v182
	v_or_b32_e32 v90, s0, v5
	v_readlane_b32 s0, v254, 30
	v_mov_b32_e32 v93, v4
	v_readlane_b32 s1, v254, 31
	v_ashrrev_i32_e32 v91, 31, v90
	v_lshlrev_b64 v[0:1], 8, v[90:91]
	v_lshl_add_u64 v[98:99], s[0:1], 0, v[92:93]
	v_lshl_add_u64 v[96:97], v[98:99], 0, v[0:1]
	v_readlane_b32 s0, v254, 34
	v_lshlrev_b64 v[94:95], 11, v[178:179]
	v_readlane_b32 s1, v254, 35
	v_or_b32_e32 v100, 32, v90
	ds_bpermute_b32 v5, v181, v194
	v_lshl_add_u64 v[94:95], s[0:1], 0, v[94:95]
	v_lshl_add_u64 v[102:103], v[94:95], 0, v[92:93]
	v_lshl_add_u64 v[124:125], v[102:103], 0, v[92:93]
	v_lshl_add_u64 v[120:121], v[96:97], 0, v[92:93]
	global_load_dwordx4 v[0:3], v[120:121], off
	global_load_dwordx4 v[70:73], v[120:121], off offset:32
	global_load_dwordx4 v[74:77], v[120:121], off offset:64
	global_load_dwordx4 v[78:81], v[120:121], off offset:96
	global_load_dwordx4 v[82:85], v[120:121], off offset:128
	global_load_dwordx4 v[86:89], v[120:121], off offset:160
	global_load_dwordx4 v[90:93], v[120:121], off offset:192
	global_load_dwordx4 v[94:97], v[120:121], off offset:224
	s_nop 0
	s_waitcnt lgkmcnt(0)
	v_add_f32_e32 v5, v194, v5
	v_div_scale_f32 v104, s[0:1], v5, v5, 1.0
	v_rcp_f32_e32 v105, v104
	v_ashrrev_i32_e32 v101, 31, v100
	v_lshlrev_b64 v[100:101], 8, v[100:101]
	v_lshl_add_u64 v[98:99], v[98:99], 0, v[100:101]
	v_lshlrev_b32_e32 v122, 1, v182
	v_mov_b32_e32 v123, v4
	v_lshl_add_u64 v[122:123], v[98:99], 0, v[122:123]
	global_load_dwordx4 v[146:149], v[122:123], off
	global_load_dwordx4 v[150:153], v[122:123], off offset:32
	global_load_dwordx4 v[154:157], v[122:123], off offset:64
	global_load_dwordx4 v[158:161], v[122:123], off offset:96
	global_load_dwordx4 v[162:165], v[122:123], off offset:128
	global_load_dwordx4 v[166:169], v[122:123], off offset:160
	global_load_dwordx4 v[170:173], v[122:123], off offset:192
	global_load_dwordx4 v[174:177], v[122:123], off offset:224
	v_fma_f32 v101, -v104, v105, 1.0
	v_div_scale_f32 v100, vcc, 1.0, v5, 1.0
	v_fmac_f32_e32 v105, v101, v105
	v_mul_f32_e32 v101, v100, v105
	v_fma_f32 v106, -v104, v101, v100
	v_fmac_f32_e32 v101, v106, v105
	v_fma_f32 v100, -v104, v101, v100
	v_div_fmas_f32 v100, v100, v105, v101
	v_div_fixup_f32 v100, v100, v5, 1.0
	v_pk_mul_f32 v[54:55], v[54:55], v[100:101] op_sel_hi:[1,0]
	v_pk_mul_f32 v[56:57], v[56:57], v[100:101] op_sel_hi:[1,0]
	v_pk_mul_f32 v[58:59], v[58:59], v[100:101] op_sel_hi:[1,0]
	v_pk_mul_f32 v[60:61], v[60:61], v[100:101] op_sel_hi:[1,0]
	v_pk_mul_f32 v[112:113], v[38:39], v[100:101] op_sel_hi:[1,0]
	v_pk_mul_f32 v[114:115], v[40:41], v[100:101] op_sel_hi:[1,0]
	v_cvt_pk_bf16_f32 v38, v54, v55
	v_cvt_pk_bf16_f32 v39, v56, v57
	v_cvt_pk_bf16_f32 v40, v58, v59
	v_cvt_pk_bf16_f32 v41, v60, v61
	v_pk_mul_f32 v[104:105], v[62:63], v[100:101] op_sel_hi:[1,0]
	v_pk_mul_f32 v[106:107], v[64:65], v[100:101] op_sel_hi:[1,0]
	v_pk_mul_f32 v[108:109], v[66:67], v[100:101] op_sel_hi:[1,0]
	v_pk_mul_f32 v[110:111], v[68:69], v[100:101] op_sel_hi:[1,0]
	v_pk_mul_f32 v[116:117], v[42:43], v[100:101] op_sel_hi:[1,0]
	v_pk_mul_f32 v[118:119], v[44:45], v[100:101] op_sel_hi:[1,0]
	v_cvt_pk_bf16_f32 v42, v112, v113
	v_cvt_pk_bf16_f32 v43, v114, v115
	v_cvt_pk_bf16_f32 v44, v116, v117
	v_cvt_pk_bf16_f32 v45, v118, v119
	v_pk_mul_f32 v[46:47], v[46:47], v[100:101] op_sel_hi:[1,0]
	v_pk_mul_f32 v[48:49], v[48:49], v[100:101] op_sel_hi:[1,0]
	v_pk_mul_f32 v[50:51], v[50:51], v[100:101] op_sel_hi:[1,0]
	v_pk_mul_f32 v[52:53], v[52:53], v[100:101] op_sel_hi:[1,0]
	v_pk_mul_f32 v[30:31], v[30:31], v[100:101] op_sel_hi:[1,0]
	v_pk_mul_f32 v[32:33], v[32:33], v[100:101] op_sel_hi:[1,0]
	v_pk_mul_f32 v[34:35], v[34:35], v[100:101] op_sel_hi:[1,0]
	v_pk_mul_f32 v[36:37], v[36:37], v[100:101] op_sel_hi:[1,0]
	v_cvt_pk_bf16_f32 v30, v30, v31
	v_cvt_pk_bf16_f32 v31, v32, v33
	v_cvt_pk_bf16_f32 v32, v34, v35
	v_cvt_pk_bf16_f32 v33, v36, v37
	v_pk_mul_f32 v[6:7], v[6:7], v[100:101] op_sel_hi:[1,0]
	v_pk_mul_f32 v[8:9], v[8:9], v[100:101] op_sel_hi:[1,0]
	v_pk_mul_f32 v[10:11], v[10:11], v[100:101] op_sel_hi:[1,0]
	v_pk_mul_f32 v[12:13], v[12:13], v[100:101] op_sel_hi:[1,0]
	v_cvt_pk_bf16_f32 v34, v6, v7
	v_cvt_pk_bf16_f32 v35, v8, v9
	s_waitcnt vmcnt(8)
; #define GAS __attribute__((address_space(1)))
; __device__ __forceinline__ unsigned pk2(float lo, float hi) { f32x2_t v = {lo, hi}; bf16x2_t b = __builtin_convertvector(v, bf16x2_t); return __builtin_bit_cast(unsigned, b); }
; __device__ __forceinline__ f32x16 mfma32(bf16x8 a, bf16x8 b, f32x16 c) { return __builtin_amdgcn_mfma_f32_32x32x16_bf16(a, b, c, 0, 0, 0); }
; __device__ __forceinline__ void dsa_unit32(const Args& a, LAS unsigned char* lds, const LAS unsigned long long* maskl, int b, int qb, int tid, int wave, int lane) {
;     ...
;     for (int vt = 0; vt < 2; ++vt) {
;         f32x16 acc;
; #pragma unroll
;         for (int i = 0; i < 16; ++i) acc[i] = 0.f;
;         const GAS bf16* wr = wuv + (size_t)(h * 64 + 32 * vt + l31) * 128 + 4 * hi;
; #pragma unroll
;         for (int ks = 0; ks < 8; ++ks) acc = mfma32(cat8(*(const GAS u32x2*)(wr + 16 * ks), *(const GAS u32x2*)(wr + 16 * ks + 8)), of[ks], acc);
; #pragma unroll
;         for (int g = 0; g < 4; ++g) { u32x2 w; w.x = pk2(acc[4 * g], acc[4 * g + 1]); w.y = pk2(acc[4 * g + 2], acc[4 * g + 3]);
;             *(GAS u32x2*)(Y + (rowb + t0 + l31) * DM + 512 + h * 64 + 32 * vt + 8 * g + 4 * hi) = w; }
;     }
	v_permlane32_swap_b32_e32 v0, v2
	v_permlane32_swap_b32_e32 v1, v3
	v_permlane32_swap_b32_e32 v70, v72
	v_permlane32_swap_b32_e32 v71, v73
	v_permlane32_swap_b32_e32 v74, v76
	v_permlane32_swap_b32_e32 v75, v77
	v_permlane32_swap_b32_e32 v78, v80
	v_permlane32_swap_b32_e32 v79, v81
	v_permlane32_swap_b32_e32 v82, v84
	v_permlane32_swap_b32_e32 v83, v85
	v_permlane32_swap_b32_e32 v86, v88
	v_permlane32_swap_b32_e32 v87, v89
	v_permlane32_swap_b32_e32 v90, v92
	v_permlane32_swap_b32_e32 v91, v93
	v_permlane32_swap_b32_e32 v94, v96
	v_permlane32_swap_b32_e32 v95, v97
	s_nop 1
	v_mfma_f32_32x32x16_bf16 v[54:69], v[0:3], v[38:41], 0
	v_cvt_pk_bf16_f32 v0, v104, v105
	v_cvt_pk_bf16_f32 v1, v106, v107
	v_cvt_pk_bf16_f32 v2, v108, v109
	v_cvt_pk_bf16_f32 v3, v110, v111
	v_cvt_pk_bf16_f32 v36, v10, v11
	v_cvt_pk_bf16_f32 v37, v12, v13
	v_pk_mul_f32 v[14:15], v[14:15], v[100:101] op_sel_hi:[1,0]
	v_mfma_f32_32x32x16_bf16 v[54:69], v[70:73], v[0:3], v[54:69]
	v_mul_f32_e64 v70, v22, v100
	v_mul_f32_e64 v71, v23, v100
	v_mul_f32_e64 v72, v24, v100
	v_mul_f32_e64 v73, v25, v100
	v_cvt_pk_bf16_f32 v22, v46, v47
	v_cvt_pk_bf16_f32 v23, v48, v49
	v_cvt_pk_bf16_f32 v24, v50, v51
	v_cvt_pk_bf16_f32 v25, v52, v53
	v_pk_mul_f32 v[6:7], v[16:17], v[100:101] op_sel_hi:[1,0]
	v_mfma_f32_32x32x16_bf16 v[54:69], v[74:77], v[42:45], v[54:69]
	v_mul_f32_e64 v74, v26, v100
	v_mul_f32_e64 v75, v27, v100
	v_mul_f32_e64 v76, v28, v100
	v_mul_f32_e64 v77, v29, v100
	v_cvt_pk_bf16_f32 v26, v70, v71
	v_cvt_pk_bf16_f32 v27, v72, v73
	v_cvt_pk_bf16_f32 v28, v74, v75
	v_cvt_pk_bf16_f32 v29, v76, v77
	v_pk_mul_f32 v[8:9], v[18:19], v[100:101] op_sel_hi:[1,0]
	v_mfma_f32_32x32x16_bf16 v[54:69], v[78:81], v[22:25], v[54:69]
	v_mul_f32_e64 v10, v20, v100
	v_mul_f32_e64 v11, v21, v100
	v_cvt_pk_bf16_f32 v46, v14, v15
	v_cvt_pk_bf16_f32 v47, v6, v7
	v_cvt_pk_bf16_f32 v48, v8, v9
	v_cvt_pk_bf16_f32 v49, v10, v11
	s_mov_b64 s[0:1], 0
	v_mfma_f32_32x32x16_bf16 v[54:69], v[82:85], v[26:29], v[54:69]
	v_mfma_f32_32x32x16_bf16 v[54:69], v[86:89], v[30:33], v[54:69]
	v_mfma_f32_32x32x16_bf16 v[54:69], v[90:93], v[34:37], v[54:69]
	v_mfma_f32_32x32x16_bf16 v[54:69], v[94:97], v[46:49], v[54:69]
	s_nop 11
	v_cvt_pk_bf16_f32 v6, v54, v55
	v_cvt_pk_bf16_f32 v7, v56, v57
	v_cvt_pk_bf16_f32 v8, v58, v59
	v_cvt_pk_bf16_f32 v9, v60, v61
	v_cvt_pk_bf16_f32 v10, v62, v63
	v_cvt_pk_bf16_f32 v11, v64, v65
	v_cvt_pk_bf16_f32 v12, v66, v67
	v_cvt_pk_bf16_f32 v13, v68, v69
	v_permlane32_swap_b32_e32 v6, v8
	v_permlane32_swap_b32_e32 v7, v9
	v_permlane32_swap_b32_e32 v10, v12
	v_permlane32_swap_b32_e32 v11, v13
	global_store_dwordx4 v[124:125], v[6:9], off offset:1024
	global_store_dwordx4 v[124:125], v[10:13], off offset:1056
	s_waitcnt vmcnt(4)
	v_permlane32_swap_b32_e32 v146, v148
	v_permlane32_swap_b32_e32 v147, v149
	v_permlane32_swap_b32_e32 v150, v152
	v_permlane32_swap_b32_e32 v151, v153
	v_permlane32_swap_b32_e32 v154, v156
	v_permlane32_swap_b32_e32 v155, v157
	v_permlane32_swap_b32_e32 v158, v160
	v_permlane32_swap_b32_e32 v159, v161
	v_permlane32_swap_b32_e32 v162, v164
	v_permlane32_swap_b32_e32 v163, v165
	v_permlane32_swap_b32_e32 v166, v168
	v_permlane32_swap_b32_e32 v167, v169
	v_permlane32_swap_b32_e32 v170, v172
	v_permlane32_swap_b32_e32 v171, v173
	v_permlane32_swap_b32_e32 v174, v176
	v_permlane32_swap_b32_e32 v175, v177
	s_nop 1
	v_mfma_f32_32x32x16_bf16 v[6:21], v[146:149], v[38:41], 0
	v_mfma_f32_32x32x16_bf16 v[6:21], v[150:153], v[0:3], v[6:21]
	v_mfma_f32_32x32x16_bf16 v[6:21], v[154:157], v[42:45], v[6:21]
	v_mfma_f32_32x32x16_bf16 v[6:21], v[158:161], v[22:25], v[6:21]
	v_mfma_f32_32x32x16_bf16 v[6:21], v[162:165], v[26:29], v[6:21]
	v_mfma_f32_32x32x16_bf16 v[6:21], v[166:169], v[30:33], v[6:21]
	v_mfma_f32_32x32x16_bf16 v[6:21], v[170:173], v[34:37], v[6:21]
	v_mfma_f32_32x32x16_bf16 v[6:21], v[174:177], v[46:49], v[6:21]
	s_nop 11
	v_cvt_pk_bf16_f32 v0, v6, v7
	v_cvt_pk_bf16_f32 v1, v8, v9
	v_cvt_pk_bf16_f32 v2, v10, v11
	v_cvt_pk_bf16_f32 v3, v12, v13
	v_cvt_pk_bf16_f32 v6, v14, v15
	v_cvt_pk_bf16_f32 v7, v16, v17
	v_cvt_pk_bf16_f32 v8, v18, v19
	v_cvt_pk_bf16_f32 v9, v20, v21
	v_permlane32_swap_b32_e32 v0, v2
	v_permlane32_swap_b32_e32 v1, v3
	v_permlane32_swap_b32_e32 v6, v8
	v_permlane32_swap_b32_e32 v7, v9
	global_store_dwordx4 v[124:125], v[0:3], off offset:1088
	global_store_dwordx4 v[124:125], v[6:9], off offset:1120
